# + m15: fused-norm epilogues drop the redundant cache invalidate after the row-statistics spin (slots are read with sc1 loads)
# speedup vs baseline: 1.0094x; 1.0016x over previous
;     __device__ __forceinline__ void run(const pg8::f32x4 (&v)[2][2][4][2], const pg8::Unit& u, int wr, int wc, int fr, int fq, LAS unsigned char* lds, int wid, int lane) const {
;     ...
;         if (wid == 0) {
;             unsigned sp = 0;
;             while ((unsigned)__builtin_amdgcn_readfirstlane(__hip_atomic_load(cnt + 64 * u.pm, __ATOMIC_RELAXED, __HIP_MEMORY_SCOPE_AGENT)) < 32u) { if (++sp > (1u << 20)) break; __builtin_amdgcn_s_sleep(0); }
;             __builtin_amdgcn_fence(__ATOMIC_ACQUIRE, "agent");
;         }
;         asm volatile("s_waitcnt vmcnt(0) lgkmcnt(0)" ::: "memory"); __builtin_amdgcn_s_barrier(); asm volatile("" ::: "memory");
;         if (lane < 32) {
;             const float* slot = xbuf + (size_t)(u.pm * 256 + row) * 4; float tot = 0.f;
; #pragma unroll
;             for (int t = 0; t < 4; ++t) tot += __hip_atomic_load(slot + t, __ATOMIC_RELAXED, __HIP_MEMORY_SCOPE_AGENT);
;             S[row] = rsqrtf(tot * (1.f / D) + EPS);
.LBB0_217:
.LBB0_218:
	s_waitcnt vmcnt(0) lgkmcnt(0)
	s_barrier
	s_and_saveexec_b64 s[14:15], s[6:7]
	s_cbranch_execz .LBB0_220
	v_lshl_add_u64 v[194:195], v[220:221], 4, s[16:17]
	global_load_dwordx4 v[240:243], v[194:195], off sc1
	v_lshl_add_u32 v192, v192, 2, 0
	s_waitcnt vmcnt(0)
	v_add_f32_e32 v196, 0, v240
	v_add_f32_e32 v196, v196, v241
	v_add_f32_e32 v196, v196, v242
	v_add_f32_e32 v194, v196, v243
	v_fmamk_f32 v194, v194, 0x3a800000, v223
	v_cmp_gt_f32_e32 vcc, s24, v194
	v_mul_f32_e32 v195, 0x4b800000, v194
	s_nop 0
	v_cndmask_b32_e32 v194, v194, v195, vcc
	v_rsq_f32_e32 v194, v194
	s_nop 0
	v_mul_f32_e32 v195, 0x45800000, v194
	v_cndmask_b32_e32 v194, v194, v195, vcc
	ds_write_b32 v192, v194 offset:8192

;     __device__ __forceinline__ void run(const pg8::f32x4 (&v)[2][2][4][2], const pg8::Unit& u, int wr, int wc, int fr, int fq, LAS unsigned char* lds, int wid, int lane) const {
;     ...
;         if (wid == 0) {
;             unsigned sp = 0;
;             while ((unsigned)__builtin_amdgcn_readfirstlane(__hip_atomic_load(cnt + 64 * u.pm, __ATOMIC_RELAXED, __HIP_MEMORY_SCOPE_AGENT)) < 32u) { if (++sp > (1u << 20)) break; __builtin_amdgcn_s_sleep(0); }
;             __builtin_amdgcn_fence(__ATOMIC_ACQUIRE, "agent");
;         }
;         asm volatile("s_waitcnt vmcnt(0) lgkmcnt(0)" ::: "memory"); __builtin_amdgcn_s_barrier(); asm volatile("" ::: "memory");
;         if (lane < 32) {
;             const float* slot = xbuf + (size_t)(u.pm * 256 + row) * 4; float tot = 0.f;
; #pragma unroll
;             for (int t = 0; t < 4; ++t) tot += __hip_atomic_load(slot + t, __ATOMIC_RELAXED, __HIP_MEMORY_SCOPE_AGENT);
;             S[row] = rsqrtf(tot * (1.f / D) + EPS);
.LBB0_272:
.LBB0_273:
	s_waitcnt vmcnt(0) lgkmcnt(0)
	s_barrier
	v_lshl_add_u32 v234, v218, 2, 0
	s_and_saveexec_b64 s[52:53], s[8:9]
	s_cbranch_execz .LBB0_275
	v_lshl_add_u64 v[194:195], v[216:217], 4, s[58:59]
	global_load_dwordx4 v[202:205], v[194:195], off sc1
	s_waitcnt vmcnt(0)
	v_add_f32_e32 v196, 0, v202
	v_add_f32_e32 v196, v196, v203
	v_add_f32_e32 v196, v196, v204
	v_add_f32_e32 v194, v196, v205
	v_fmamk_f32 v194, v194, 0x3a800000, v223
	v_cmp_gt_f32_e32 vcc, s24, v194
	v_mul_f32_e32 v195, 0x4b800000, v194
	s_nop 0
	v_cndmask_b32_e32 v194, v194, v195, vcc
	v_rsq_f32_e32 v194, v194
	s_nop 0
	v_mul_f32_e32 v195, 0x45800000, v194
	v_cndmask_b32_e32 v194, v194, v195, vcc
	ds_write_b32 v234, v194 offset:8192

;     __device__ __forceinline__ void run(const pg8::f32x4 (&v)[2][2][4][2], const pg8::Unit& u, int wr, int wc, int fr, int fq, LAS unsigned char* lds, int wid, int lane) const {
;     ...
;         if (wid == 0) {
;             unsigned sp = 0;
;             while ((unsigned)__builtin_amdgcn_readfirstlane(__hip_atomic_load(cnt + 64 * u.pm, __ATOMIC_RELAXED, __HIP_MEMORY_SCOPE_AGENT)) < 32u) { if (++sp > (1u << 20)) break; __builtin_amdgcn_s_sleep(0); }
;             __builtin_amdgcn_fence(__ATOMIC_ACQUIRE, "agent");
;         }
;         asm volatile("s_waitcnt vmcnt(0) lgkmcnt(0)" ::: "memory"); __builtin_amdgcn_s_barrier(); asm volatile("" ::: "memory");
;         if (lane < 32) {
;             const float* slot = xbuf + (size_t)(u.pm * 256 + row) * 4; float tot = 0.f;
; #pragma unroll
;             for (int t = 0; t < 4; ++t) tot += __hip_atomic_load(slot + t, __ATOMIC_RELAXED, __HIP_MEMORY_SCOPE_AGENT);
;             S[row] = rsqrtf(tot * (1.f / D) + EPS);
.LBB0_301:
.LBB0_302:
	s_waitcnt vmcnt(0) lgkmcnt(0)
	s_barrier
	s_and_saveexec_b64 s[10:11], s[8:9]
	s_cbranch_execz .LBB0_304
	s_waitcnt lgkmcnt(0)
	v_lshl_add_u64 v[128:129], v[216:217], 4, s[6:7]
	global_load_dwordx4 v[236:239], v[128:129], off sc1
	s_waitcnt vmcnt(0)
	v_add_f32_e32 v130, 0, v236
	v_add_f32_e32 v130, v130, v237
	v_add_f32_e32 v130, v130, v238
	v_add_f32_e32 v128, v130, v239
	v_fmamk_f32 v128, v128, 0x3a800000, v223
	v_cmp_gt_f32_e32 vcc, s24, v128
	v_mul_f32_e32 v129, 0x4b800000, v128
	s_nop 0
	v_cndmask_b32_e32 v128, v128, v129, vcc
	v_rsq_f32_e32 v128, v128
	s_nop 0
	v_mul_f32_e32 v129, 0x45800000, v128
	v_cndmask_b32_e32 v128, v128, v129, vcc
	ds_write_b32 v234, v128 offset:8192
